# f12 + gla_out second unit loads prefetched into spare registers during first unit compute
# baseline (speedup 1.0000x reference)
; #define LAS __attribute__((address_space(3)))
; #define MFMA32(a, b, c) __builtin_amdgcn_mfma_f32_32x32x16_bf16((a), (b), (c), 0, 0, 0)
; __device__ __forceinline__ void gla_out_unit(Frame& F, int bh, int n) {
;     ...
;     f32x16 acc[2];
; #pragma unroll
;     for (int lb = 0; lb < 2; ++lb)
; #pragma unroll
;         for (int i = 0; i < 16; ++i) acc[lb][i] = 0.f;
; #pragma unroll
;     for (int s = 0; s < 8; ++s)
; #pragma unroll
;         for (int lb = 0; lb < 2; ++lb) { const bf16x8 qf = *(const LAS bf16x8*)(lds + GL_KT + (32 * lb + r) * 272 + (16 * s + 8 * h) * 2); acc[lb] = MFMA32(qf, sf[s], acc[lb]); }
;     __syncthreads();
; #pragma unroll
;     for (int s = 0; s < 4; ++s) { const bf16x8 vf = trfrag(lds + GL_VT + (16 * s + 8 * h + q4) * VST + (32 * wid + 16 * b16 + 4 * p4) * 2, 4 * VST);
; #pragma unroll
;         for (int lb = 0; lb < 2; ++lb) { const bf16x8 af = *(const LAS bf16x8*)(lds + GL_ATT + (32 * lb + r) * PST + (16 * s + 8 * h) * 2); acc[lb] = MFMA32(af, vf, acc[lb]); } }
; __global__ void __launch_bounds__(NWAVES * 64, 2) mk_fwd(Args args) {
;     ...
;         xcd_wait(bar);
;         for (int u = F.vcu; u < 512; u += G) gla_out_unit(F, u >> 6, u & 63);
.LBB0_794:
	s_or_b64 exec, exec, s[4:5]
	s_andn2_b64 vcc, exec, s[0:1]
	s_waitcnt lgkmcnt(0)
	s_barrier
	s_cbranch_vccnz .LBB0_809
	v_readlane_b32 s0, v252, 10
	s_lshl_b32 s3, s0, 5
	s_add_u32 s12, s34, 0x8000000
	s_addc_u32 s13, s35, 0
	v_readlane_b32 s4, v252, 7
	s_cmpk_gt_u32 s4, 0xff
	s_cselect_b64 s[0:1], -1, 0
	s_lshr_b32 s4, s4, 7
	s_lshl_b32 s19, s4, 5
	s_lshl_b32 s4, s4, 6
	s_add_i32 s23, s4, 0
	s_ashr_i32 s83, s82, 31
	s_and_b32 s22, s3, 32
	s_add_i32 s23, s23, 0x1a400
	s_lshl_b64 s[8:9], s[82:83], 16
	s_add_u32 s4, s34, s8
	s_addc_u32 s9, s35, s9
	s_add_u32 s8, s4, 0x5a00000
	s_addc_u32 s9, s9, 0
	s_ashr_i32 s15, s14, 31
	v_mbcnt_lo_u32_b32 v2, -1, 0
	s_mov_b32 s5, 0
	s_lshl_b64 s[10:11], s[14:15], 16
	s_lshl_b32 s15, s82, 6
	s_lshl_b32 s24, s14, 6
	s_movk_i32 s25, 0x3c00
	v_mov_b32_e32 v83, 0
	s_mov_b64 s[16:17], 0x1000
	s_movk_i32 s26, 0x100
	s_add_i32 s27, 0, 0x1d000
	s_movk_i32 s28, 0x110
	s_add_i32 s29, 0, 0x11000
	s_add_i32 s33, 0, 0x16000
	s_mov_b32 s18, 0x3db504f3
	s_movk_i32 s36, 0x90
	s_movk_i32 s37, 0x240
	v_mov_b32_e32 v86, 0x358637bd
	v_mov_b32_e32 v87, 0x80
	v_mov_b32_e32 v88, 0x1200
	v_mbcnt_hi_u32_b32 v89, -1, v2
	s_mov_b32 s101, 0
	s_mov_b32 s100, 0
	v_mov_b32_e32 v244, 0
	v_mov_b32_e32 v245, 0
	v_mov_b32_e32 v246, 0
	v_mov_b32_e32 v247, 0
	s_cmpk_lg_i32 s14, 0x100
	s_cbranch_scc1 .Lgo_init_done
	s_add_i32 s98, s82, s14
	s_cmpk_gt_i32 s98, 0x1ff
	s_cbranch_scc1 .Lgo_init_done
	s_mov_b32 s100, 1
	v_mov_b32_e32 v244, s10
	v_mov_b32_e32 v245, s11
	v_mov_b32_e32 v246, 0x3c00000
.Lgo_init_done:
	s_branch .LBB0_797
.LBB0_796:
	v_mul_u32_u24_e32 v2, 0x110, v92
	v_add3_u32 v97, s29, v96, v2
	ds_read_b128 v[2:5], v97
	ds_read_b128 v[98:101], v97 offset:32
	s_add_i32 s20, 0, 0x1a400
	s_add_i32 s82, s82, s14
	s_waitcnt lgkmcnt(1)
	v_mfma_f32_32x32x16_bf16 v[18:33], v[2:5], v[78:81], 0
	ds_read_b128 v[2:5], v97 offset:8704
	ds_read_b128 v[102:105], v97 offset:8736
	s_waitcnt lgkmcnt(1)
	v_mfma_f32_32x32x16_bf16 v[2:17], v[2:5], v[78:81], 0
	v_mfma_f32_32x32x16_bf16 v[18:33], v[98:101], v[74:77], v[18:33]
	s_waitcnt lgkmcnt(0)
	v_mfma_f32_32x32x16_bf16 v[2:17], v[102:105], v[74:77], v[2:17]
	ds_read_b128 v[74:77], v97 offset:64
	ds_read_b128 v[78:81], v97 offset:96
	s_waitcnt lgkmcnt(1)
	v_mfma_f32_32x32x16_bf16 v[18:33], v[74:77], v[70:73], v[18:33]
	ds_read_b128 v[74:77], v97 offset:8768
	ds_read_b128 v[98:101], v97 offset:8800
	s_waitcnt lgkmcnt(1)
	v_mfma_f32_32x32x16_bf16 v[2:17], v[74:77], v[70:73], v[2:17]
	v_mfma_f32_32x32x16_bf16 v[18:33], v[78:81], v[66:69], v[18:33]
	s_waitcnt lgkmcnt(0)
	v_mfma_f32_32x32x16_bf16 v[2:17], v[98:101], v[66:69], v[2:17]
	ds_read_b128 v[66:69], v97 offset:128
	ds_read_b128 v[70:73], v97 offset:160
	s_waitcnt lgkmcnt(1)
	v_mfma_f32_32x32x16_bf16 v[18:33], v[66:69], v[62:65], v[18:33]
	ds_read_b128 v[66:69], v97 offset:8832
	ds_read_b128 v[74:77], v97 offset:8864
	s_waitcnt lgkmcnt(1)
	v_mfma_f32_32x32x16_bf16 v[2:17], v[66:69], v[62:65], v[2:17]
	v_mfma_f32_32x32x16_bf16 v[18:33], v[70:73], v[58:61], v[18:33]
	v_bfe_u32 v70, v84, 2, 2
	v_or_b32_e32 v71, 32, v95
	s_waitcnt lgkmcnt(0)
	v_mfma_f32_32x32x16_bf16 v[2:17], v[74:77], v[58:61], v[2:17]
	ds_read_b128 v[58:61], v97 offset:192
	ds_read_b128 v[62:65], v97 offset:224
	v_mad_u32_u24 v75, v92, s36, v88
	s_waitcnt lgkmcnt(1)
	v_mfma_f32_32x32x16_bf16 v[18:33], v[58:61], v[54:57], v[18:33]
	ds_read_b128 v[58:61], v97 offset:8896
	ds_read_b128 v[66:69], v97 offset:8928
	s_waitcnt lgkmcnt(0)
	s_barrier
	v_mfma_f32_32x32x16_bf16 v[2:17], v[58:61], v[54:57], v[2:17]
	v_and_b32_e32 v54, 16, v84
	v_and_b32_e32 v55, 12, v93
	v_or3_b32 v54, v54, v55, s3
	v_lshl_add_u32 v74, v54, 1, 0
	v_or_b32_e32 v54, v95, v70
	v_add_u32_e32 v59, s20, v96
	v_mad_u32_u24 v58, v54, s37, v74
	v_mad_u32_u24 v54, v92, s36, v59
	ds_read_b128 v[54:57], v54
	v_mfma_f32_32x32x16_bf16 v[18:33], v[62:65], v[50:53], v[18:33]
	v_or_b32_e32 v62, 16, v95
	v_or_b32_e32 v63, v62, v70
	v_mad_u32_u24 v63, v63, s37, v74
	v_lshl_add_u32 v62, v62, 1, s20
	v_mfma_f32_32x32x16_bf16 v[2:17], v[66:69], v[50:53], v[2:17]
	ds_read_b64_tr_b16 v[50:51], v58 offset:32768
	ds_read_b64_tr_b16 v[52:53], v58 offset:35072
	v_add_u32_e32 v58, v59, v75
	ds_read_b128 v[58:61], v58
	v_add_u32_e32 v66, v62, v75
	s_waitcnt lgkmcnt(1)
	v_mfma_f32_32x32x16_bf16 v[18:33], v[54:57], v[50:53], v[18:33]
	ds_read_b64_tr_b16 v[54:55], v63 offset:32768
	ds_read_b64_tr_b16 v[56:57], v63 offset:35072
	v_mad_u32_u24 v63, v92, s36, v62
	ds_read_b128 v[62:65], v63
	ds_read_b128 v[66:69], v66
	s_waitcnt lgkmcnt(4)
	v_mfma_f32_32x32x16_bf16 v[2:17], v[58:61], v[50:53], v[2:17]
	v_or_b32_e32 v50, v71, v70
	v_lshl_add_u32 v71, v71, 1, s20
	v_mad_u32_u24 v52, v50, s37, v74
	v_mad_u32_u24 v58, v92, s36, v71
	ds_read_b64_tr_b16 v[50:51], v52 offset:32768
	ds_read_b64_tr_b16 v[52:53], v52 offset:35072
	ds_read_b128 v[58:61], v58
	s_waitcnt lgkmcnt(4)
	v_mfma_f32_32x32x16_bf16 v[18:33], v[62:65], v[54:57], v[18:33]
	v_add_u32_e32 v62, v71, v75
	ds_read_b128 v[62:65], v62
	v_or_b32_e32 v71, 48, v95
	v_lshl_add_u32 v77, v71, 1, s20
	v_or_b32_e32 v76, v71, v70
	v_mad_u32_u24 v70, v92, s36, v77
	ds_read_b128 v[70:73], v70
	s_waitcnt lgkmcnt(5)
	v_mfma_f32_32x32x16_bf16 v[2:17], v[66:69], v[54:57], v[2:17]
	s_waitcnt lgkmcnt(2)
	v_mfma_f32_32x32x16_bf16 v[18:33], v[58:61], v[50:53], v[18:33]
	v_mad_u32_u24 v60, v76, s37, v74
	v_add_u32_e32 v74, v77, v75
	ds_read_b64_tr_b16 v[58:59], v60 offset:32768
	ds_read_b64_tr_b16 v[60:61], v60 offset:35072
	ds_read_b128 v[74:77], v74
	s_waitcnt lgkmcnt(4)
	v_mfma_f32_32x32x16_bf16 v[2:17], v[62:65], v[50:53], v[2:17]
	s_waitcnt vmcnt(23)
	v_lshlrev_b32_e32 v62, 16, v46
	v_and_b32_e32 v63, 0xffff0000, v46
	s_waitcnt lgkmcnt(1)
; #define LAS __attribute__((address_space(3)))
; __device__ __forceinline__ float frsq(float x) { return __builtin_amdgcn_rsqf(x); }
; __device__ __forceinline__ int crow(int r, int hi) { return (r & 3) + 8 * (r >> 2) + 4 * hi; }
; #define MFMA32(a, b, c) __builtin_amdgcn_mfma_f32_32x32x16_bf16((a), (b), (c), 0, 0, 0)
; __device__ __forceinline__ void gla_out_unit(Frame& F, int bh, int n) {
;     ...
; #pragma unroll
;     for (int s = 0; s < 4; ++s) { const bf16x8 vf = trfrag(lds + GL_VT + (16 * s + 8 * h + q4) * VST + (32 * wid + 16 * b16 + 4 * p4) * 2, 4 * VST);
; #pragma unroll
;         for (int lb = 0; lb < 2; ++lb) { const bf16x8 af = *(const LAS bf16x8*)(lds + GL_ATT + (32 * lb + r) * PST + (16 * s + 8 * h) * 2); acc[lb] = MFMA32(af, vf, acc[lb]); } }
; #pragma unroll
;     for (int lb = 0; lb < 2; ++lb)
; #pragma unroll
;         for (int i = 0; i < 16; ++i) { const int lr = crow(i, h);
;             *(LAS float*)(lds + (lb ? GL_GY : GL_LA) + lr * 1024 + (((32 * wid + r) * 4) ^ ((lr & 1) << 4))) = acc[lb][i]; }
;     __syncthreads();
;     { const int l = tid >> 3, sw = (l & 1) << 4;
;       const LAS unsigned char* orow = lds + ((l & 32) ? GL_GY : GL_LA) + (l & 31) * 1024;
;       const LAS f32x4* gnt = (const LAS f32x4*)(lds + GL_RED);
;       f32x4 o[4][2]; float ss = 0.f;
; #pragma unroll
;       for (int i = 0; i < 4; ++i) { const int c = (tid & 7) + 8 * i;
;           o[i][0] = *(const LAS f32x4*)(orow + ((c * 32) ^ sw)); o[i][1] = *(const LAS f32x4*)(orow + ((c * 32 + 16) ^ sw));
; #pragma unroll
;           for (int e = 0; e < 4; ++e) ss += o[i][0][e] * o[i][0][e] + o[i][1][e] * o[i][1][e]; }
;       ss += __shfl_xor(ss, 1); ss += __shfl_xor(ss, 2); ss += __shfl_xor(ss, 4);
;       const float rn = frsq(ss * (1.0f / 256.0f) + NORM_EPS);
	v_mfma_f32_32x32x16_bf16 v[18:33], v[70:73], v[58:61], v[18:33]
	v_lshl_add_u32 v70, v94, 12, 0
	v_lshlrev_b32_e32 v71, 2, v82
	v_add_u32_e32 v72, v70, v71
	v_lshlrev_b32_e32 v82, 1, v85
	s_waitcnt lgkmcnt(0)
	v_mfma_f32_32x32x16_bf16 v[2:17], v[74:77], v[58:61], v[2:17]
	s_nop 5
	ds_write_b32 v72, v18
	v_xad_u32 v18, v71, 16, v70
	ds_write_b32 v18, v19 offset:1024
	ds_write_b32 v72, v20 offset:2048
	v_add_u32_e32 v19, 0x1d800, v72
	ds_write_b32 v18, v21 offset:3072
	ds_write_b32 v72, v22 offset:8192
	ds_write_b32 v18, v23 offset:9216
	ds_write_b32 v72, v24 offset:10240
	ds_write_b32 v18, v25 offset:11264
	ds_write_b32 v72, v26 offset:16384
	ds_write_b32 v18, v27 offset:17408
	ds_write_b32 v72, v28 offset:18432
	ds_write_b32 v18, v29 offset:19456
	ds_write_b32 v72, v30 offset:24576
	ds_write_b32 v18, v31 offset:25600
	ds_write_b32 v72, v32 offset:26624
	ds_write_b32 v18, v33 offset:27648
	ds_write_b32 v19, v2
	v_add_u32_e32 v2, 0x1dc00, v18
	ds_write_b32 v2, v3
	v_add_u32_e32 v2, 0x1e000, v72
	ds_write_b32 v2, v4
	v_add_u32_e32 v2, 0x1e400, v18
	ds_write_b32 v2, v5
	v_add_u32_e32 v2, 0x1f800, v72
	ds_write_b32 v2, v6
	v_add_u32_e32 v2, 0x1fc00, v18
	ds_write_b32 v2, v7
	v_add_u32_e32 v2, 0x20000, v72
	ds_write_b32 v2, v8
	v_add_u32_e32 v2, 0x20400, v18
	ds_write_b32 v2, v9
	v_add_u32_e32 v2, 0x21800, v72
	ds_write_b32 v2, v10
	v_add_u32_e32 v2, 0x21c00, v18
	ds_write_b32 v2, v11
	v_add_u32_e32 v2, 0x22000, v72
	ds_write_b32 v2, v12
	v_add_u32_e32 v2, 0x22400, v18
	ds_write_b32 v2, v13
	v_add_u32_e32 v2, 0x23800, v72
	ds_write_b32 v2, v14
	v_add_u32_e32 v2, 0x23c00, v18
	ds_write_b32 v2, v15
	v_add_u32_e32 v2, 0x24000, v72
	ds_write_b32 v2, v16
	v_add_u32_e32 v2, 0x24400, v18
	v_bfe_i32 v3, v84, 8, 1
	v_lshlrev_b32_e32 v4, 10, v90
	ds_write_b32 v2, v17
	v_lshlrev_b32_e32 v2, 4, v90
	v_and_b32_e32 v3, 0x1d800, v3
	v_and_b32_e32 v4, 0x7c00, v4
	v_and_b32_e32 v2, 16, v2
	v_add3_u32 v3, 0, v3, v4
	v_or_b32_e32 v4, 16, v91
	v_xad_u32 v4, v4, v2, v3
	s_waitcnt lgkmcnt(0)
	s_barrier
	v_add3_u32 v6, v3, v2, v91
	ds_read_b128 v[30:33], v4
	ds_read_b128 v[50:53], v6
	v_or_b32_e32 v4, 0x110, v91
	v_xad_u32 v4, v4, v2, v3
	ds_read_b128 v[18:21], v4
	ds_read_b128 v[22:25], v6 offset:256
	s_waitcnt lgkmcnt(3)
	v_mul_f32_e32 v4, v30, v30
	v_mul_f32_e32 v5, v31, v31
	s_waitcnt lgkmcnt(2)
	v_fmac_f32_e32 v4, v50, v50
	v_fmac_f32_e32 v5, v51, v51
	v_add_f32_e32 v4, v4, v5
	v_mul_f32_e32 v5, v32, v32
	v_fmac_f32_e32 v5, v52, v52
	v_add_f32_e32 v4, v5, v4
	v_mul_f32_e32 v5, v33, v33
	v_fmac_f32_e32 v5, v53, v53
	v_add_f32_e32 v4, v5, v4
	s_waitcnt lgkmcnt(1)
	v_mul_f32_e32 v5, v18, v18
	s_waitcnt lgkmcnt(0)
	v_fmac_f32_e32 v5, v22, v22
	v_add_f32_e32 v4, v5, v4
	v_mul_f32_e32 v5, v19, v19
	v_fmac_f32_e32 v5, v23, v23
	v_add_f32_e32 v4, v5, v4
	v_mul_f32_e32 v5, v20, v20
	v_fmac_f32_e32 v5, v24, v24
	v_add_f32_e32 v4, v5, v4
	v_mul_f32_e32 v5, v21, v21
	v_fmac_f32_e32 v5, v25, v25
	v_add_f32_e32 v26, v5, v4
	v_or_b32_e32 v4, 0x210, v91
	v_xad_u32 v4, v4, v2, v3
	ds_read_b128 v[10:13], v4
	ds_read_b128 v[14:17], v6 offset:512
	v_or_b32_e32 v4, 0x310, v91
	v_xad_u32 v2, v4, v2, v3
	ds_read_b128 v[2:5], v2
	ds_read_b128 v[6:9], v6 offset:768
	s_waitcnt lgkmcnt(3)
	v_mul_f32_e32 v27, v10, v10
	s_waitcnt lgkmcnt(2)
	v_fmac_f32_e32 v27, v14, v14
	v_add_f32_e32 v26, v27, v26
	v_mul_f32_e32 v27, v11, v11
	v_fmac_f32_e32 v27, v15, v15
	v_add_f32_e32 v28, v27, v26
	v_pk_mul_f32 v[26:27], v[12:13], v[12:13]
	s_nop 0
	v_pk_fma_f32 v[26:27], v[16:17], v[16:17], v[26:27]
	s_nop 0
	v_add_f32_e32 v26, v26, v28
	s_waitcnt lgkmcnt(1)
	v_pk_mul_f32 v[28:29], v[2:3], v[2:3]
	v_add_f32_e32 v54, v27, v26
	s_waitcnt lgkmcnt(0)
	v_pk_fma_f32 v[28:29], v[6:7], v[6:7], v[28:29]
	v_pk_mul_f32 v[26:27], v[4:5], v[4:5]
	v_add_f32_e32 v28, v28, v54
	v_pk_fma_f32 v[26:27], v[8:9], v[8:9], v[26:27]
	v_add_f32_e32 v28, v29, v28
	v_add_f32_e32 v26, v26, v28
	v_and_b32_e32 v28, 64, v89
	v_add_f32_e32 v26, v27, v26
	v_xor_b32_e32 v27, 1, v89
	v_add_u32_e32 v28, 64, v28
	v_cmp_lt_i32_e32 vcc, v27, v28
	v_mul_f32_e32 v54, 0xbfb8aa3b, v62
	v_exp_f32_e32 v64, v54
	v_cndmask_b32_e32 v27, v89, v27, vcc
	v_lshlrev_b32_e32 v27, 2, v27
	ds_bpermute_b32 v27, v27, v26
	v_add_f32_e32 v46, 1.0, v64
	v_mul_f32_e32 v64, 0xbfb8aa3b, v63
	v_exp_f32_e32 v65, v64
	v_add_u32_e32 v29, 0, v91
	s_waitcnt lgkmcnt(0)
	v_add_f32_e32 v26, v26, v27
	v_xor_b32_e32 v27, 2, v89
	v_cmp_lt_i32_e32 vcc, v27, v28
	v_add_u32_e32 v29, 0x1c800, v29
	ds_read_b128 v[54:57], v29
	ds_read_b128 v[58:61], v29 offset:16
	v_cndmask_b32_e32 v27, v89, v27, vcc
	v_lshlrev_b32_e32 v27, 2, v27
	ds_bpermute_b32 v27, v27, v26
	v_rcp_f32_e32 v64, v46
	v_add_f32_e32 v46, 1.0, v65
	v_rcp_f32_e32 v65, v46
	v_lshlrev_b32_e32 v46, 16, v47
	s_waitcnt lgkmcnt(0)
	v_add_f32_e32 v26, v26, v27
	v_xor_b32_e32 v27, 4, v89
	v_cmp_lt_i32_e32 vcc, v27, v28
	v_and_b32_e32 v47, 0xffff0000, v47
	s_nop 0
	v_cndmask_b32_e32 v27, v89, v27, vcc
	v_lshlrev_b32_e32 v27, 2, v27
	ds_bpermute_b32 v27, v27, v26
	s_waitcnt lgkmcnt(0)
; __device__ __forceinline__ unsigned pk2(float lo, float hi) { f32x2 v = {lo, hi}; bf16x2_t b = __builtin_convertvector(v, bf16x2_t); return __builtin_bit_cast(unsigned, b); }
; __device__ __forceinline__ float bflo(unsigned u) { return __uint_as_float(u << 16); }
; __device__ __forceinline__ float bfhi(unsigned u) { return __uint_as_float(u & 0xffff0000u); }
; __device__ __forceinline__ float frsq(float x) { return __builtin_amdgcn_rsqf(x); }
; __device__ __forceinline__ float sigmoidf_(float x) { return frcp(1.0f + fexp(-x)); }
; __device__ __forceinline__ void gla_out_unit(Frame& F, int bh, int n) {
;     ...
;       ss += __shfl_xor(ss, 1); ss += __shfl_xor(ss, 2); ss += __shfl_xor(ss, 4);
;       const float rn = frsq(ss * (1.0f / 256.0f) + NORM_EPS);
;       bf16* Y = (bf16*)F.out + (size_t)(b * SEQ + 64 * n + l) * 1024 + hd * 256 + (tid & 7) * 8;
; #pragma unroll
;       for (int i = 0; i < 4; ++i) { const int c = (tid & 7) + 8 * i;
;           const f32x4 g0 = gnt[2 * c], g1 = gnt[2 * c + 1];
;           const unsigned gw[4] = {gr[i].x, gr[i].y, gr[i].z, gr[i].w};
;           float y[8];
; #pragma unroll
;           for (int e = 0; e < 4; ++e) { const float ga = bflo(gw[e]), gb = bfhi(gw[e]);
;               const float oa = (e < 2) ? o[i][0][2 * e] : o[i][1][2 * e - 4], ob = (e < 2) ? o[i][0][2 * e + 1] : o[i][1][2 * e - 3];
;               const float na = (e < 2) ? g0[2 * e] : g1[2 * e - 4], nb = (e < 2) ? g0[2 * e + 1] : g1[2 * e - 3];
;               y[2 * e] = oa * rn * na * (ga * sigmoidf_(ga)); y[2 * e + 1] = ob * rn * nb * (gb * sigmoidf_(gb)); }
;           u32x4 w; w.x = pk2(y[0], y[1]); w.y = pk2(y[2], y[3]); w.z = pk2(y[4], y[5]); w.w = pk2(y[6], y[7]);
;           *(u32x4*)(Y + 64 * i) = w; } }
	v_add_f32_e32 v26, v26, v27
	v_fmamk_f32 v26, v26, 0x3b800000, v86
	v_rsq_f32_e32 v28, v26
	v_add_u32_e32 v26, s4, v90
	v_ashrrev_i32_e32 v27, 31, v26
	v_lshlrev_b64 v[26:27], 11, v[26:27]
	v_pk_mul_f32 v[50:51], v[50:51], v[28:29] op_sel_hi:[1,0]
	v_pk_mul_f32 v[52:53], v[52:53], v[28:29] op_sel_hi:[1,0]
	v_pk_mul_f32 v[50:51], v[54:55], v[50:51]
	v_mul_f32_e32 v54, 0xbfb8aa3b, v46
	v_exp_f32_e32 v66, v54
	v_pk_mul_f32 v[54:55], v[64:65], v[62:63]
	v_pk_mul_f32 v[52:53], v[56:57], v[52:53]
	v_pk_mul_f32 v[50:51], v[54:55], v[50:51]
	v_mul_f32_e32 v55, 0xbfb8aa3b, v47
	v_exp_f32_e32 v55, v55
	v_add_f32_e32 v54, 1.0, v66
	v_rcp_f32_e32 v54, v54
	v_lshlrev_b32_e32 v56, 16, v48
	v_add_f32_e32 v55, 1.0, v55
	v_rcp_f32_e32 v55, v55
	v_mul_f32_e32 v57, 0xbfb8aa3b, v56
	v_exp_f32_e32 v62, v57
	v_and_b32_e32 v57, 0xffff0000, v48
	v_pk_mul_f32 v[46:47], v[54:55], v[46:47]
	v_pk_mul_f32 v[30:31], v[30:31], v[28:29] op_sel_hi:[1,0]
	v_pk_mul_f32 v[46:47], v[46:47], v[52:53]
	v_mul_f32_e32 v52, 0xbfb8aa3b, v57
	v_exp_f32_e32 v53, v52
	v_add_f32_e32 v48, 1.0, v62
	v_rcp_f32_e32 v52, v48
	v_pk_mul_f32 v[30:31], v[58:59], v[30:31]
	v_add_f32_e32 v48, 1.0, v53
	v_rcp_f32_e32 v53, v48
	v_lshlrev_b32_e32 v48, 16, v49
	v_and_b32_e32 v49, 0xffff0000, v49
	v_mul_f32_e32 v54, 0xbfb8aa3b, v48
	v_mul_f32_e32 v55, 0xbfb8aa3b, v49
	v_exp_f32_e32 v54, v54
	v_exp_f32_e32 v55, v55
	v_pk_mul_f32 v[52:53], v[52:53], v[56:57]
	v_lshl_add_u64 v[26:27], s[70:71], 0, v[26:27]
	v_add_f32_e32 v54, 1.0, v54
	v_add_f32_e32 v55, 1.0, v55
	v_rcp_f32_e32 v54, v54
	v_rcp_f32_e32 v55, v55
	v_pk_mul_f32 v[52:53], v[52:53], v[30:31]
	v_pk_mul_f32 v[30:31], v[32:33], v[28:29] op_sel_hi:[1,0]
	s_lshl_b32 s4, s38, 1
	v_pk_mul_f32 v[30:31], v[60:61], v[30:31]
	v_pk_mul_f32 v[32:33], v[54:55], v[48:49]
	v_lshl_add_u64 v[26:27], v[26:27], 0, s[4:5]
	v_pk_mul_f32 v[48:49], v[32:33], v[30:31]
	v_lshl_add_u64 v[26:27], v[26:27], 0, v[82:83]
	v_cvt_pk_bf16_f32 v30, v50, v51
	v_cvt_pk_bf16_f32 v31, v46, v47
	v_cvt_pk_bf16_f32 v32, v52, v53
	v_cvt_pk_bf16_f32 v33, v48, v49
	v_lshlrev_b32_e32 v50, 16, v42
	global_store_dwordx4 v[26:27], v[30:33], off
	v_and_b32_e32 v51, 0xffff0000, v42
	v_pk_mul_f32 v[22:23], v[22:23], v[28:29] op_sel_hi:[1,0]
	v_mul_f32_e32 v30, 0xbfb8aa3b, v50
	v_exp_f32_e32 v52, v30
	ds_read_b128 v[30:33], v29 offset:256
	ds_read_b128 v[46:49], v29 offset:272
	v_pk_mul_f32 v[24:25], v[24:25], v[28:29] op_sel_hi:[1,0]
	v_pk_mul_f32 v[18:19], v[18:19], v[28:29] op_sel_hi:[1,0]
	v_add_f32_e32 v42, 1.0, v52
	v_mul_f32_e32 v52, 0xbfb8aa3b, v51
	v_exp_f32_e32 v53, v52
	s_waitcnt lgkmcnt(1)
	v_pk_mul_f32 v[22:23], v[30:31], v[22:23]
	v_rcp_f32_e32 v52, v42
	v_pk_mul_f32 v[24:25], v[32:33], v[24:25]
	v_add_f32_e32 v30, 1.0, v53
	v_rcp_f32_e32 v53, v30
	v_lshlrev_b32_e32 v30, 16, v43
	v_mul_f32_e32 v31, 0xbfb8aa3b, v30
	v_exp_f32_e32 v42, v31
	v_and_b32_e32 v31, 0xffff0000, v43
	v_mul_f32_e32 v43, 0xbfb8aa3b, v31
	v_exp_f32_e32 v43, v43
	v_add_f32_e32 v42, 1.0, v42
	v_rcp_f32_e32 v42, v42
	v_pk_mul_f32 v[50:51], v[52:53], v[50:51]
	v_add_f32_e32 v32, 1.0, v43
	v_rcp_f32_e32 v43, v32
	v_lshlrev_b32_e32 v32, 16, v44
	v_mul_f32_e32 v33, 0xbfb8aa3b, v32
	v_pk_mul_f32 v[22:23], v[50:51], v[22:23]
	v_exp_f32_e32 v50, v33
	v_pk_mul_f32 v[30:31], v[42:43], v[30:31]
	v_and_b32_e32 v33, 0xffff0000, v44
	v_pk_mul_f32 v[24:25], v[30:31], v[24:25]
	v_mul_f32_e32 v31, 0xbfb8aa3b, v33
	v_exp_f32_e32 v31, v31
	v_lshlrev_b32_e32 v42, 16, v45
	v_and_b32_e32 v43, 0xffff0000, v45
	v_add_f32_e32 v30, 1.0, v50
	v_add_f32_e32 v31, 1.0, v31
	v_mul_f32_e32 v44, 0xbfb8aa3b, v42
	v_mul_f32_e32 v45, 0xbfb8aa3b, v43
	v_rcp_f32_e32 v30, v30
	v_rcp_f32_e32 v31, v31
	v_exp_f32_e32 v44, v44
	v_exp_f32_e32 v45, v45
	s_waitcnt lgkmcnt(0)
	v_pk_mul_f32 v[18:19], v[46:47], v[18:19]
	v_pk_mul_f32 v[30:31], v[30:31], v[32:33]
	v_add_f32_e32 v32, 1.0, v44
	v_add_f32_e32 v33, 1.0, v45
	v_rcp_f32_e32 v32, v32
	v_rcp_f32_e32 v33, v33
	v_pk_mul_f32 v[30:31], v[30:31], v[18:19]
	v_pk_mul_f32 v[18:19], v[20:21], v[28:29] op_sel_hi:[1,0]
	v_pk_mul_f32 v[14:15], v[14:15], v[28:29] op_sel_hi:[1,0]
	v_pk_mul_f32 v[18:19], v[48:49], v[18:19]
	v_pk_mul_f32 v[20:21], v[32:33], v[42:43]
	v_pk_mul_f32 v[16:17], v[16:17], v[28:29] op_sel_hi:[1,0]
	v_pk_mul_f32 v[32:33], v[20:21], v[18:19]
	v_cvt_pk_bf16_f32 v18, v22, v23
	v_cvt_pk_bf16_f32 v19, v24, v25
	v_cvt_pk_bf16_f32 v20, v30, v31
	v_cvt_pk_bf16_f32 v21, v32, v33
	v_lshlrev_b32_e32 v30, 16, v38
	v_and_b32_e32 v31, 0xffff0000, v38
	global_store_dwordx4 v[26:27], v[18:21], off offset:128
	v_mul_f32_e32 v33, 0xbfb8aa3b, v31
	v_exp_f32_e32 v33, v33
	v_mul_f32_e32 v18, 0xbfb8aa3b, v30
	v_exp_f32_e32 v32, v18
	ds_read_b128 v[18:21], v29 offset:512
	ds_read_b128 v[22:25], v29 offset:528
	v_pk_mul_f32 v[10:11], v[10:11], v[28:29] op_sel_hi:[1,0]
	v_pk_mul_f32 v[6:7], v[6:7], v[28:29] op_sel_hi:[1,0]
	v_add_f32_e32 v32, 1.0, v32
	s_waitcnt lgkmcnt(1)
	v_pk_mul_f32 v[14:15], v[18:19], v[14:15]
	v_add_f32_e32 v18, 1.0, v33
	v_rcp_f32_e32 v32, v32
	v_rcp_f32_e32 v33, v18
	v_lshlrev_b32_e32 v18, 16, v39
	v_mul_f32_e32 v19, 0xbfb8aa3b, v18
	v_exp_f32_e32 v38, v19
	v_pk_mul_f32 v[30:31], v[32:33], v[30:31]
	v_and_b32_e32 v19, 0xffff0000, v39
	v_pk_mul_f32 v[14:15], v[30:31], v[14:15]
	v_mul_f32_e32 v31, 0xbfb8aa3b, v19
	v_exp_f32_e32 v31, v31
	v_add_f32_e32 v30, 1.0, v38
	v_pk_mul_f32 v[16:17], v[20:21], v[16:17]
	v_rcp_f32_e32 v30, v30
	v_add_f32_e32 v20, 1.0, v31
	v_rcp_f32_e32 v31, v20
	v_lshlrev_b32_e32 v20, 16, v40
	v_mul_f32_e32 v21, 0xbfb8aa3b, v20
	v_exp_f32_e32 v32, v21
	v_pk_mul_f32 v[18:19], v[30:31], v[18:19]
	v_and_b32_e32 v21, 0xffff0000, v40
	v_pk_mul_f32 v[16:17], v[18:19], v[16:17]
	v_mul_f32_e32 v19, 0xbfb8aa3b, v21
	v_exp_f32_e32 v19, v19
	s_waitcnt lgkmcnt(0)
; __device__ __forceinline__ unsigned pk2(float lo, float hi) { f32x2 v = {lo, hi}; bf16x2_t b = __builtin_convertvector(v, bf16x2_t); return __builtin_bit_cast(unsigned, b); }
; __device__ __forceinline__ float bflo(unsigned u) { return __uint_as_float(u << 16); }
; __device__ __forceinline__ float bfhi(unsigned u) { return __uint_as_float(u & 0xffff0000u); }
; __device__ __forceinline__ float sigmoidf_(float x) { return frcp(1.0f + fexp(-x)); }
; __device__ __forceinline__ void gla_out_unit(Frame& F, int bh, int n) {
;     ...
;     const bf16* sb = WSP(bf16, WS_SB) + (size_t)(bh * 64 + n) * 256 * 128 + (size_t)(32 * wid + r) * 128 + 8 * h;
;     bf16x8 sf[8];
; #pragma unroll
;     for (int s = 0; s < 8; ++s) sf[s] = *(const bf16x8*)(sb + 16 * s);
;     gla_load_la(lds, zrow + ZA_GLA + hd * 128, tid);
;     u32x4 qr[2], kr[2];
;     { const bf16* p = zrow + ZQ_GLA + hd * 128 + (size_t)(tid >> 3) * NZ + (tid & 7) * 8; qr[0] = *(const u32x4*)p; qr[1] = *(const u32x4*)(p + 64); }
;     { const bf16* p = zrow + ZK_GLA + hd * 128 + (size_t)(tid >> 3) * NZ + (tid & 7) * 8; kr[0] = *(const u32x4*)p; kr[1] = *(const u32x4*)(p + 64); }
;     { u32x4 vr[4]; tile_load(vr, zrow + ZV_GLA + hd * 256, NZ, tid); tile_store_raw(vr, lds + GL_VT, tid); }
;     u32x4 gr[4]; tile_load(gr, zrow + ZG_GLA + hd * 256, NZ, tid);
;     ...
;       bf16* Y = (bf16*)F.out + (size_t)(b * SEQ + 64 * n + l) * 1024 + hd * 256 + (tid & 7) * 8;
; #pragma unroll
;       for (int i = 0; i < 4; ++i) { const int c = (tid & 7) + 8 * i;
;           const f32x4 g0 = gnt[2 * c], g1 = gnt[2 * c + 1];
;           const unsigned gw[4] = {gr[i].x, gr[i].y, gr[i].z, gr[i].w};
;           float y[8];
; #pragma unroll
;           for (int e = 0; e < 4; ++e) { const float ga = bflo(gw[e]), gb = bfhi(gw[e]);
;               const float oa = (e < 2) ? o[i][0][2 * e] : o[i][1][2 * e - 4], ob = (e < 2) ? o[i][0][2 * e + 1] : o[i][1][2 * e - 3];
;               const float na = (e < 2) ? g0[2 * e] : g1[2 * e - 4], nb = (e < 2) ? g0[2 * e + 1] : g1[2 * e - 3];
;               y[2 * e] = oa * rn * na * (ga * sigmoidf_(ga)); y[2 * e + 1] = ob * rn * nb * (gb * sigmoidf_(gb)); }
;           u32x4 w; w.x = pk2(y[0], y[1]); w.y = pk2(y[2], y[3]); w.z = pk2(y[4], y[5]); w.w = pk2(y[6], y[7]);
;           *(u32x4*)(Y + 64 * i) = w; } }
	v_pk_mul_f32 v[10:11], v[22:23], v[10:11]
	v_lshlrev_b32_e32 v22, 16, v41
	v_and_b32_e32 v23, 0xffff0000, v41
	v_add_f32_e32 v18, 1.0, v32
	v_add_f32_e32 v19, 1.0, v19
	v_mul_f32_e32 v30, 0xbfb8aa3b, v22
	v_mul_f32_e32 v31, 0xbfb8aa3b, v23
	v_rcp_f32_e32 v18, v18
	v_rcp_f32_e32 v19, v19
	v_exp_f32_e32 v30, v30
	v_exp_f32_e32 v31, v31
	v_pk_mul_f32 v[8:9], v[8:9], v[28:29] op_sel_hi:[1,0]
	v_pk_mul_f32 v[18:19], v[18:19], v[20:21]
	v_add_f32_e32 v20, 1.0, v30
	v_add_f32_e32 v21, 1.0, v31
	v_rcp_f32_e32 v20, v20
	v_rcp_f32_e32 v21, v21
	v_pk_mul_f32 v[18:19], v[18:19], v[10:11]
	v_pk_mul_f32 v[10:11], v[12:13], v[28:29] op_sel_hi:[1,0]
	v_pk_mul_f32 v[2:3], v[2:3], v[28:29] op_sel_hi:[1,0]
	v_pk_mul_f32 v[10:11], v[24:25], v[10:11]
	v_pk_mul_f32 v[12:13], v[20:21], v[22:23]
	s_add_u32 s8, s8, s10
	v_pk_mul_f32 v[20:21], v[12:13], v[10:11]
	v_cvt_pk_bf16_f32 v12, v18, v19
	s_waitcnt vmcnt(24)
	v_lshlrev_b32_e32 v18, 16, v34
	v_and_b32_e32 v19, 0xffff0000, v34
	v_mul_f32_e32 v13, 0xbfb8aa3b, v18
	v_cvt_pk_bf16_f32 v10, v14, v15
	v_exp_f32_e32 v14, v13
	v_mul_f32_e32 v13, 0xbfb8aa3b, v19
	v_exp_f32_e32 v15, v13
	v_cvt_pk_bf16_f32 v13, v20, v21
	v_add_f32_e32 v14, 1.0, v14
	v_rcp_f32_e32 v20, v14
	v_add_f32_e32 v14, 1.0, v15
	v_cvt_pk_bf16_f32 v11, v16, v17
	v_rcp_f32_e32 v21, v14
	ds_read_b128 v[14:17], v29 offset:768
	global_store_dwordx4 v[26:27], v[10:13], off offset:256
	ds_read_b128 v[10:13], v29 offset:784
	v_pk_mul_f32 v[18:19], v[20:21], v[18:19]
	s_addc_u32 s9, s9, s11
	s_waitcnt lgkmcnt(1)
	v_pk_mul_f32 v[6:7], v[14:15], v[6:7]
	v_lshlrev_b32_e32 v14, 16, v35
	v_and_b32_e32 v15, 0xffff0000, v35
	v_mul_f32_e32 v20, 0xbfb8aa3b, v14
	v_mul_f32_e32 v21, 0xbfb8aa3b, v15
	v_exp_f32_e32 v20, v20
	v_exp_f32_e32 v21, v21
	v_pk_mul_f32 v[6:7], v[18:19], v[6:7]
	v_pk_mul_f32 v[8:9], v[16:17], v[8:9]
	v_add_f32_e32 v18, 1.0, v20
	v_add_f32_e32 v19, 1.0, v21
	v_lshlrev_b32_e32 v20, 16, v36
	v_and_b32_e32 v21, 0xffff0000, v36
	v_mul_f32_e32 v22, 0xbfb8aa3b, v20
	v_mul_f32_e32 v23, 0xbfb8aa3b, v21
	v_rcp_f32_e32 v18, v18
	v_rcp_f32_e32 v19, v19
	v_exp_f32_e32 v22, v22
	v_exp_f32_e32 v23, v23
	v_lshlrev_b32_e32 v16, 16, v37
	v_pk_mul_f32 v[14:15], v[18:19], v[14:15]
	v_add_f32_e32 v18, 1.0, v22
	v_add_f32_e32 v19, 1.0, v23
	v_rcp_f32_e32 v18, v18
	v_rcp_f32_e32 v19, v19
	v_and_b32_e32 v17, 0xffff0000, v37
	v_pk_mul_f32 v[8:9], v[14:15], v[8:9]
	s_waitcnt lgkmcnt(0)
	v_pk_mul_f32 v[2:3], v[10:11], v[2:3]
	v_pk_mul_f32 v[14:15], v[18:19], v[20:21]
	v_mul_f32_e32 v18, 0xbfb8aa3b, v16
	v_mul_f32_e32 v19, 0xbfb8aa3b, v17
	v_exp_f32_e32 v18, v18
	v_exp_f32_e32 v19, v19
	v_pk_mul_f32 v[14:15], v[14:15], v[2:3]
	v_pk_mul_f32 v[2:3], v[4:5], v[28:29] op_sel_hi:[1,0]
	v_add_f32_e32 v10, 1.0, v18
	v_add_f32_e32 v11, 1.0, v19
	v_rcp_f32_e32 v10, v10
	v_rcp_f32_e32 v11, v11
	v_pk_mul_f32 v[2:3], v[12:13], v[2:3]
	s_add_i32 s15, s15, s24
	s_cmpk_gt_i32 s82, 0x1ff
	v_pk_mul_f32 v[4:5], v[10:11], v[16:17]
	s_nop 0
	v_pk_mul_f32 v[10:11], v[4:5], v[2:3]
	v_cvt_pk_bf16_f32 v2, v6, v7
	v_cvt_pk_bf16_f32 v3, v8, v9
	v_cvt_pk_bf16_f32 v4, v14, v15
	v_cvt_pk_bf16_f32 v5, v10, v11
	global_store_dwordx4 v[26:27], v[2:5], off offset:384
	s_barrier
	s_cbranch_scc1 .LBB0_809
.LBB0_797:
	s_cmp_eq_u32 s101, 1
	s_cbranch_scc1 .Lgo_mov
	v_and_b32_e32 v251, 0xff, v0
	v_lshlrev_b32_e32 v251, 2, v251
	global_load_dword v250, v251, s[30:31]
	s_ashr_i32 s20, s82, 6
	s_lshl_b32 s4, s20, 10
	s_and_b32 s4, s4, 0xfffff000
	s_and_b32 s21, s15, 0xfc0
	s_or_b32 s4, s4, s21
	s_mul_i32 s38, s4, 0x3c00
	s_and_b32 s39, s20, 3
	v_mov_b32_e32 v84, v0
	s_mul_hi_i32 s21, s4, 0x3c00
	s_add_u32 s42, s12, s38
	s_addc_u32 s43, s13, s21
	v_and_b32_e32 v92, 31, v84
	s_lshl_b32 s38, s39, 8
	v_or_b32_e32 v82, s3, v92
	s_add_u32 s20, s42, s38
	v_lshlrev_b64 v[2:3], 8, v[82:83]
	v_lshrrev_b32_e32 v4, 1, v84
	s_addc_u32 s21, s43, 0
	v_and_or_b32 v2, v4, 16, v2
	s_add_u32 s40, s20, 0x3800
	v_lshl_add_u64 v[2:3], s[8:9], 0, v[2:3]
	s_addc_u32 s41, s21, 0
	v_lshl_add_u64 v[232:233], v[2:3], 0, v[244:245]
	global_load_dwordx4 v[78:81], v[2:3], off
	global_load_dwordx4 v[74:77], v[2:3], off offset:32
	global_load_dwordx4 v[70:73], v[2:3], off offset:64
	global_load_dwordx4 v[66:69], v[2:3], off offset:96
	global_load_dwordx4 v[62:65], v[2:3], off offset:128
	global_load_dwordx4 v[58:61], v[2:3], off offset:160
	global_load_dwordx4 v[54:57], v[2:3], off offset:192
	global_load_dwordx4 v[50:53], v[2:3], off offset:224
	v_ashrrev_i32_e32 v90, 3, v84
	v_mov_b64_e32 v[2:3], s[40:41]
	v_and_b32_e32 v22, 7, v84
	v_mad_i64_i32 v[2:3], s[40:41], v90, s25, v[2:3]
	v_lshlrev_b32_e32 v18, 4, v22
	v_mov_b32_e32 v19, v83
	v_lshl_add_u64 v[2:3], v[2:3], 0, v[18:19]
	v_lshl_add_u64 v[234:235], v[2:3], 0, v[246:247]
	global_load_dwordx4 v[24:27], v[2:3], off
	global_load_dwordx4 v[28:31], v[2:3], off offset:128
	v_mov_b64_e32 v[2:3], s[20:21]
	v_mad_i64_i32 v[2:3], s[20:21], v90, s25, v[2:3]
	s_lshl_b32 s20, s39, 9
	s_add_u32 s20, s42, s20
	s_addc_u32 s21, s43, 0
	v_lshl_add_u64 v[2:3], v[2:3], 0, v[18:19]
	v_mov_b64_e32 v[20:21], s[20:21]
	v_lshlrev_b32_e32 v19, 4, v84
	v_mad_i64_i32 v[20:21], s[20:21], v90, s25, v[20:21]
	v_and_b32_e32 v32, 0x70, v19
	v_mov_b32_e32 v33, v83
	v_lshl_add_u64 v[20:21], v[20:21], 0, v[32:33]
	v_lshl_add_u64 v[236:237], v[2:3], 0, v[246:247]
	global_load_dwordx4 v[14:17], v[2:3], off
	global_load_dwordx4 v[6:9], v[2:3], off offset:128
	global_load_dwordx4 v[10:13], v[2:3], off offset:1024
	s_nop 0
	global_load_dwordx4 v[2:5], v[2:3], off offset:1152
	s_nop 0
	v_lshl_add_u64 v[238:239], v[20:21], 0, v[246:247]
	global_load_dwordx4 v[94:97], v[20:21], off offset:2048
	global_load_dwordx4 v[98:101], v[20:21], off offset:2176
; #define LAS __attribute__((address_space(3)))
; __device__ __forceinline__ float bflo(unsigned u) { return __uint_as_float(u << 16); }
; __device__ __forceinline__ float bfhi(unsigned u) { return __uint_as_float(u & 0xffff0000u); }
; __device__ __forceinline__ void gla_load_la(LAS unsigned char* lds, const bf16* src, int tid) {
;     const bf16* p = src + (size_t)(tid >> 3) * NZ + (tid & 7) * 8;
; #pragma unroll
;     for (int i = 0; i < 2; ++i) { const u32x4 v = *(const u32x4*)(p + 64 * i); LAS float* d = (LAS float*)(lds + GL_LA) + (tid >> 3) * 128 + ((tid & 7) + 8 * i) * 8;
;         *(LAS f32x4*)d = (f32x4){bflo(v.x), bfhi(v.x), bflo(v.y), bfhi(v.y)}; *(LAS f32x4*)(d + 4) = (f32x4){bflo(v.z), bfhi(v.z), bflo(v.w), bfhi(v.w)}; }
; __device__ __forceinline__ void gla_out_unit(Frame& F, int bh, int n) {
;     ...
;     const bf16* sb = WSP(bf16, WS_SB) + (size_t)(bh * 64 + n) * 256 * 128 + (size_t)(32 * wid + r) * 128 + 8 * h;
;     bf16x8 sf[8];
; #pragma unroll
;     for (int s = 0; s < 8; ++s) sf[s] = *(const bf16x8*)(sb + 16 * s);
;     gla_load_la(lds, zrow + ZA_GLA + hd * 128, tid);
;     u32x4 qr[2], kr[2];
;     { const bf16* p = zrow + ZQ_GLA + hd * 128 + (size_t)(tid >> 3) * NZ + (tid & 7) * 8; qr[0] = *(const u32x4*)p; qr[1] = *(const u32x4*)(p + 64); }
;     { const bf16* p = zrow + ZK_GLA + hd * 128 + (size_t)(tid >> 3) * NZ + (tid & 7) * 8; kr[0] = *(const u32x4*)p; kr[1] = *(const u32x4*)(p + 64); }
;     { u32x4 vr[4]; tile_load(vr, zrow + ZV_GLA + hd * 256, NZ, tid); tile_store_raw(vr, lds + GL_VT, tid); }
;     u32x4 gr[4]; tile_load(gr, zrow + ZG_GLA + hd * 256, NZ, tid);
;     if (tid < 256) ((LAS float*)(lds + GL_RED))[tid] = F.in[7][tid];
	global_load_dwordx4 v[102:105], v[20:21], off offset:2304
	global_load_dwordx4 v[106:109], v[20:21], off offset:2432
	v_lshl_add_u64 v[34:35], v[20:21], 0, s[16:17]
	v_add_co_u32_e32 v20, vcc, 0x1000, v20
	v_lshl_add_u32 v19, v90, 9, 0
	s_nop 0
	v_addc_co_u32_e32 v21, vcc, 0, v21, vcc
	v_lshl_add_u64 v[240:241], v[34:35], 0, v[246:247]
	global_load_dwordx4 v[42:45], v[34:35], off offset:128
	global_load_dwordx4 v[38:41], v[34:35], off offset:256
	v_lshl_add_u64 v[242:243], v[20:21], 0, v[246:247]
	global_load_dwordx4 v[46:49], v[20:21], off
	s_nop 0
	global_load_dwordx4 v[34:37], v[34:35], off offset:384
	global_load_dwordx4 v[198:201], v[232:233], off
	global_load_dwordx4 v[194:197], v[232:233], off offset:32
	global_load_dwordx4 v[190:193], v[232:233], off offset:64
	global_load_dwordx4 v[186:189], v[232:233], off offset:96
	global_load_dwordx4 v[182:185], v[232:233], off offset:128
	global_load_dwordx4 v[178:181], v[232:233], off offset:160
	global_load_dwordx4 v[174:177], v[232:233], off offset:192
	global_load_dwordx4 v[170:173], v[232:233], off offset:224
	global_load_dwordx4 v[144:147], v[234:235], off
	global_load_dwordx4 v[148:151], v[234:235], off offset:128
	global_load_dwordx4 v[134:137], v[236:237], off
	global_load_dwordx4 v[126:129], v[236:237], off offset:128
	global_load_dwordx4 v[130:133], v[236:237], off offset:1024
	global_load_dwordx4 v[122:125], v[236:237], off offset:1152
	global_load_dwordx4 v[214:217], v[238:239], off offset:2048
	global_load_dwordx4 v[218:221], v[238:239], off offset:2176
	global_load_dwordx4 v[222:225], v[238:239], off offset:2304
	global_load_dwordx4 v[226:229], v[238:239], off offset:2432
	global_load_dwordx4 v[162:165], v[240:241], off offset:128
	global_load_dwordx4 v[158:161], v[240:241], off offset:256
	global_load_dwordx4 v[166:169], v[242:243], off
	global_load_dwordx4 v[154:157], v[240:241], off offset:384
	s_mov_b32 s101, s100
	s_branch .Lgo_join
.Lgo_mov:
	v_and_b32_e32 v251, 0xff, v0
	v_lshlrev_b32_e32 v251, 2, v251
	global_load_dword v250, v251, s[30:31]
	s_waitcnt vmcnt(0)
	s_ashr_i32 s20, s82, 6
	s_lshl_b32 s4, s20, 10
	s_and_b32 s4, s4, 0xfffff000
	s_and_b32 s21, s15, 0xfc0
	s_or_b32 s4, s4, s21
	s_mul_i32 s38, s4, 0x3c00
	s_and_b32 s39, s20, 3
	v_mov_b32_e32 v84, v0
	s_mul_hi_i32 s21, s4, 0x3c00
	s_add_u32 s42, s12, s38
	s_addc_u32 s43, s13, s21
	v_and_b32_e32 v92, 31, v84
	s_lshl_b32 s38, s39, 8
	v_or_b32_e32 v82, s3, v92
	s_add_u32 s20, s42, s38
	v_lshlrev_b64 v[2:3], 8, v[82:83]
	v_lshrrev_b32_e32 v4, 1, v84
	s_addc_u32 s21, s43, 0
	v_and_or_b32 v2, v4, 16, v2
	s_add_u32 s40, s20, 0x3800
	v_lshl_add_u64 v[2:3], s[8:9], 0, v[2:3]
	s_addc_u32 s41, s21, 0
	v_mov_b64_e32 v[78:79], v[198:199]
	v_mov_b64_e32 v[80:81], v[200:201]
	v_mov_b64_e32 v[74:75], v[194:195]
	v_mov_b64_e32 v[76:77], v[196:197]
	v_mov_b64_e32 v[70:71], v[190:191]
	v_mov_b64_e32 v[72:73], v[192:193]
	v_mov_b64_e32 v[66:67], v[186:187]
	v_mov_b64_e32 v[68:69], v[188:189]
	v_mov_b64_e32 v[62:63], v[182:183]
	v_mov_b64_e32 v[64:65], v[184:185]
	v_mov_b64_e32 v[58:59], v[178:179]
	v_mov_b64_e32 v[60:61], v[180:181]
	v_mov_b64_e32 v[54:55], v[174:175]
	v_mov_b64_e32 v[56:57], v[176:177]
	v_mov_b64_e32 v[50:51], v[170:171]
	v_mov_b64_e32 v[52:53], v[172:173]
	v_ashrrev_i32_e32 v90, 3, v84
	v_mov_b64_e32 v[2:3], s[40:41]
	v_and_b32_e32 v22, 7, v84
	v_mad_i64_i32 v[2:3], s[40:41], v90, s25, v[2:3]
	v_lshlrev_b32_e32 v18, 4, v22
	v_mov_b32_e32 v19, v83
	v_lshl_add_u64 v[2:3], v[2:3], 0, v[18:19]
	v_mov_b64_e32 v[24:25], v[144:145]
	v_mov_b64_e32 v[26:27], v[146:147]
	v_mov_b64_e32 v[28:29], v[148:149]
	v_mov_b64_e32 v[30:31], v[150:151]
	v_mov_b64_e32 v[2:3], s[20:21]
	v_mad_i64_i32 v[2:3], s[20:21], v90, s25, v[2:3]
	s_lshl_b32 s20, s39, 9
	s_add_u32 s20, s42, s20
	s_addc_u32 s21, s43, 0
	v_lshl_add_u64 v[2:3], v[2:3], 0, v[18:19]
	v_mov_b64_e32 v[20:21], s[20:21]
	v_lshlrev_b32_e32 v19, 4, v84
	v_mad_i64_i32 v[20:21], s[20:21], v90, s25, v[20:21]
	v_and_b32_e32 v32, 0x70, v19
	v_mov_b32_e32 v33, v83
	v_lshl_add_u64 v[20:21], v[20:21], 0, v[32:33]
	v_mov_b64_e32 v[14:15], v[134:135]
	v_mov_b64_e32 v[16:17], v[136:137]
	v_mov_b64_e32 v[6:7], v[126:127]
	v_mov_b64_e32 v[8:9], v[128:129]
	v_mov_b64_e32 v[10:11], v[130:131]
	v_mov_b64_e32 v[12:13], v[132:133]
	s_nop 0
	v_mov_b64_e32 v[2:3], v[122:123]
	v_mov_b64_e32 v[4:5], v[124:125]
	s_nop 0
	v_mov_b64_e32 v[94:95], v[214:215]
	v_mov_b64_e32 v[96:97], v[216:217]
	v_mov_b64_e32 v[98:99], v[218:219]
	v_mov_b64_e32 v[100:101], v[220:221]
	v_mov_b64_e32 v[102:103], v[222:223]
	v_mov_b64_e32 v[104:105], v[224:225]
	v_mov_b64_e32 v[106:107], v[226:227]
	v_mov_b64_e32 v[108:109], v[228:229]
	v_lshl_add_u64 v[34:35], v[20:21], 0, s[16:17]
	v_add_co_u32_e32 v20, vcc, 0x1000, v20
	v_lshl_add_u32 v19, v90, 9, 0
	s_nop 0
	v_addc_co_u32_e32 v21, vcc, 0, v21, vcc
	v_mov_b64_e32 v[42:43], v[162:163]
	v_mov_b64_e32 v[44:45], v[164:165]
	v_mov_b64_e32 v[38:39], v[158:159]
	v_mov_b64_e32 v[40:41], v[160:161]
	v_mov_b64_e32 v[46:47], v[166:167]
	v_mov_b64_e32 v[48:49], v[168:169]
	s_nop 0
	v_mov_b64_e32 v[34:35], v[154:155]
	v_mov_b64_e32 v[36:37], v[156:157]
.Lgo_join:
	v_lshlrev_b32_e32 v91, 5, v22
	v_add_u32_e32 v20, v19, v91
	v_cmp_gt_i32_e32 vcc, s26, v84
	s_waitcnt vmcnt(35)
	v_lshlrev_b32_e32 v110, 16, v24
	v_and_b32_e32 v111, 0xffff0000, v24
	v_lshlrev_b32_e32 v112, 16, v25
	v_and_b32_e32 v113, 0xffff0000, v25
	v_lshlrev_b32_e32 v24, 16, v26
	v_and_b32_e32 v25, 0xffff0000, v26
	v_lshlrev_b32_e32 v26, 16, v27
	v_and_b32_e32 v27, 0xffff0000, v27
	s_waitcnt vmcnt(34)
	v_lshlrev_b32_e32 v114, 16, v28
	v_and_b32_e32 v115, 0xffff0000, v28
	v_lshlrev_b32_e32 v116, 16, v29
	v_and_b32_e32 v117, 0xffff0000, v29
	v_lshlrev_b32_e32 v28, 16, v30
	v_and_b32_e32 v29, 0xffff0000, v30
	v_lshlrev_b32_e32 v30, 16, v31
	v_and_b32_e32 v31, 0xffff0000, v31
	ds_write_b128 v20, v[110:113]
	ds_write_b128 v20, v[24:27] offset:16
	ds_write_b128 v20, v[114:117] offset:256
	ds_write_b128 v20, v[28:31] offset:272
	v_lshlrev_b32_e32 v20, 6, v90
	v_add3_u32 v20, v19, v20, v32
	s_waitcnt vmcnt(29)
	ds_write_b128 v20, v[94:97] offset:32768
	s_waitcnt vmcnt(28)
	ds_write_b128 v20, v[98:101] offset:32896
	s_waitcnt vmcnt(27)
	ds_write_b128 v20, v[102:105] offset:33024
	s_waitcnt vmcnt(26)
	ds_write_b128 v20, v[106:109] offset:33152
	s_and_saveexec_b64 s[20:21], vcc
	s_cbranch_execz .LBB0_799
	v_ashrrev_i32_e32 v85, 31, v84
	v_lshl_add_u32 v21, v84, 2, 0
	v_add_u32_e32 v21, 0x1c800, v21
	ds_write_b32 v21, v250
